# hand-written p0_weights: next item loads issued before LDS reads/stores (bit-identical weights)
# speedup vs baseline: 1.0069x; 1.0069x over previous
.LBB0_61:
	s_lshl_b32 s0, s9, 3
	v_readlane_b32 s1, v255, 21
	s_add_i32 s4, s0, s1
	s_lshl_b32 s0, s72, 3
	v_writelane_b32 v255, s0, 22
	s_cmp_gt_i32 s4, 0x12fff
	s_nop 0
	v_writelane_b32 v255, s1, 23
	s_mov_b32 s0, s4
	v_writelane_b32 v255, s0, 24
	s_barrier
	s_nop 0
	v_writelane_b32 v255, s1, 25
	s_cbranch_scc1 .LBB0_95
	v_lshrrev_b32_e32 v40, 3, v55
	v_and_b32_e32 v41, 7, v55
	v_readlane_b32 s5, v255, 21
	v_readlane_b32 s30, v255, 22
	v_readlane_b32 s20, v255, 9
	v_readlane_b32 s21, v255, 10
	v_readlane_b32 s22, v255, 11
	v_readlane_b32 s23, v255, 12
	v_readlane_b32 s24, v255, 7
	v_readlane_b32 s25, v255, 8
	v_readlane_b32 s26, v255, 3
	v_readlane_b32 s27, v255, 4
	v_readlane_b32 s28, v255, 5
	v_readlane_b32 s29, v255, 6
	v_lshlrev_b32_e32 v44, 2, v40
	v_lshlrev_b32_e32 v43, 4, v41
	s_lshl_b32 s5, s5, 14
	v_mul_u32_u24_e32 v42, 0x84, v40
	v_mul_u32_u24_e32 v45, 0x420, v41
	v_add3_u32 v42, v42, v43, s5
	v_add3_u32 v45, v45, v44, s5
	s_mov_b32 s51, s4

	s_cmp_ge_u32 s51, 0x9800
	s_cselect_b32 s10, 1, 0
	s_mul_i32 s11, s10, 0x9800
	s_sub_u32 s11, s51, s11
	s_mul_i32 s12, s10, 0xa000000
	s_add_u32 s66, s3, s12
	s_addc_u32 s67, s8, 0
	s_mov_b32 s69, 0
	s_cmp_lt_u32 s11, 0x5800
	s_cbranch_scc0 .Lpw_notgu_a
	s_cmp_ge_u32 s11, 0x2c00
	s_cselect_b32 s13, 1, 0
	s_cselect_b32 s60, s20, s44
	s_cselect_b32 s61, s21, s45
	s_mul_i32 s14, s13, 0x2c00
	s_sub_u32 s11, s11, s14
	s_mul_hi_u32 s15, s11, 0xba2e8c
	s_mul_i32 s14, s15, 0x160
	s_sub_u32 s16, s11, s14
	s_lshl_b32 s16, s16, 5
	s_mul_i32 s14, s10, 0x5800000
	s_add_u32 s60, s60, s14
	s_addc_u32 s61, s61, 0
	s_mul_i32 s14, s15, 0x2c0000
	s_add_u32 s60, s60, s14
	s_addc_u32 s61, s61, 0
	s_lshl_b32 s14, s16, 2
	s_add_u32 s60, s60, s14
	s_addc_u32 s61, s61, 0
	s_mov_b32 s62, 0xb000
	s_mov_b32 s63, 0x58000
	s_cmp_ge_u32 s16, 0x1600
	s_cselect_b32 s17, 1, 0
	s_mul_i32 s18, s17, 0x1600
	s_sub_u32 s18, s16, s18
	s_lshr_b32 s19, s18, 7
	s_lshl_b32 s19, s19, 8
	s_lshl_b32 s14, s17, 7
	s_add_u32 s19, s19, s14
	s_and_b32 s14, s18, 0x7f
	s_add_u32 s19, s19, s14
	s_mul_i32 s14, s13, 0x2c00000
	s_add_u32 s66, s66, s14
	s_addc_u32 s67, s67, 0
	s_lshl_b32 s14, s19, 12
	s_add_u32 s66, s66, s14
	s_addc_u32 s67, s67, 0
	s_lshl_b32 s14, s15, 7
	s_add_u32 s66, s66, s14
	s_addc_u32 s67, s67, 0
	s_movk_i32 s68, 0x1000
	s_mov_b32 s70, 0x8000
	s_branch .Lpw_pdone_a
.Lpw_notgu_a:
	s_cmp_lt_u32 s11, 0x8400
	s_cbranch_scc0 .Lpw_notd_a
	s_sub_u32 s11, s11, 0x5800
	s_cmp_ge_u32 s11, 0x1600
	s_cselect_b32 s13, 1, 0
	s_cselect_b32 s60, s22, s46
	s_cselect_b32 s61, s23, s47
	s_mul_i32 s14, s13, 0x1600
	s_sub_u32 s11, s11, s14
	s_lshr_b32 s15, s11, 6
	s_and_b32 s16, s11, 63
	s_mul_i32 s14, s10, 0x2c00000
	s_add_u32 s60, s60, s14
	s_addc_u32 s61, s61, 0
	s_lshl_b32 s14, s15, 19
	s_add_u32 s60, s60, s14
	s_addc_u32 s61, s61, 0
	s_lshl_b32 s14, s16, 7
	s_add_u32 s60, s60, s14
	s_addc_u32 s61, s61, 0
	s_movk_i32 s62, 0x2000
	s_mov_b32 s63, 0x10000
	s_mul_i32 s14, s13, 0x1600000
	s_add_u32 s14, s14, 0x5800000
	s_add_u32 s66, s66, s14
	s_addc_u32 s67, s67, 0
	s_mul_i32 s14, s16, 0x58000
	s_add_u32 s66, s66, s14
	s_addc_u32 s67, s67, 0
	s_lshl_b32 s14, s15, 7
	s_add_u32 s66, s66, s14
	s_addc_u32 s67, s67, 0
	s_mov_b32 s68, 0x2c00
	s_mov_b32 s70, 0x16000
	s_branch .Lpw_pdone_a
.Lpw_notd_a:
	s_cmp_lt_u32 s11, 0x9000
	s_cbranch_scc0 .Lpw_o_a
	s_sub_u32 s11, s11, 0x8400
	s_mul_hi_u32 s15, s11, 0x2aaaaab
	s_mul_i32 s14, s15, 0x60
	s_sub_u32 s16, s11, s14
	s_lshl_b32 s16, s16, 5
	s_mul_i32 s14, s10, 0x2000000
	s_add_u32 s60, s48, s14
	s_addc_u32 s61, s49, 0
	s_lshl_b32 s14, s15, 20
	s_add_u32 s60, s60, s14
	s_addc_u32 s61, s61, 0
	s_lshl_b32 s14, s16, 2
	s_add_u32 s14, s14, 0x1000
	s_add_u32 s60, s60, s14
	s_addc_u32 s61, s61, 0
	s_movk_i32 s62, 0x4000
	s_mov_b32 s63, 0x20000
	s_lshr_b32 s17, s16, 10
	s_and_b32 s18, s16, 0x3ff
	s_cmp_eq_u32 s17, 2
	s_cbranch_scc1 .Lpw_v_a
	s_lshr_b32 s19, s18, 7
	s_and_b32 s31, s18, 0x7f
	s_lshl_b32 s33, s17, 10
	s_lshr_b32 s14, s19, 1
	s_lshl_b32 s14, s14, 8
	s_add_u32 s33, s33, s14
	s_lshr_b32 s14, s31, 6
	s_lshl_b32 s14, s14, 7
	s_add_u32 s33, s33, s14
	s_and_b32 s14, s19, 1
	s_lshl_b32 s14, s14, 6
	s_add_u32 s33, s33, s14
	s_and_b32 s14, s31, 63
	s_add_u32 s33, s33, s14
	s_branch .Lpw_vd_a
.Lpw_v_a:
	s_add_u32 s33, s18, 0x800
.Lpw_vd_a:
	s_add_u32 s66, s66, 0x8c00000
	s_addc_u32 s67, s67, 0
	s_lshl_b32 s14, s33, 12
	s_add_u32 s66, s66, s14
	s_addc_u32 s67, s67, 0
	s_lshl_b32 s14, s15, 7
	s_add_u32 s66, s66, s14
	s_addc_u32 s67, s67, 0
	s_movk_i32 s68, 0x1000
	s_mov_b32 s70, 0x8000
	s_branch .Lpw_pdone_a
.Lpw_o_a:
	s_sub_u32 s11, s11, 0x9000
	s_lshr_b32 s15, s11, 6
	s_and_b32 s16, s11, 63
	s_lshl_b32 s14, s10, 24
	s_add_u32 s60, s24, s14
	s_addc_u32 s61, s25, 0
	s_lshl_b32 s14, s15, 19
	s_add_u32 s60, s60, s14
	s_addc_u32 s61, s61, 0
	s_lshl_b32 s14, s16, 7
	s_add_u32 s60, s60, s14
	s_addc_u32 s61, s61, 0
	s_movk_i32 s62, 0x2000
	s_mov_b32 s63, 0x10000
	s_add_u32 s66, s66, 0x9800000
	s_addc_u32 s67, s67, 0
	s_lshl_b32 s14, s16, 17
	s_add_u32 s66, s66, s14
	s_addc_u32 s67, s67, 0
	s_lshl_b32 s14, s15, 7
	s_add_u32 s66, s66, s14
	s_addc_u32 s67, s67, 0
	s_movk_i32 s68, 0x1000
	s_mov_b32 s70, 0x8000
	s_cmp_lt_u32 s15, 16
	s_cselect_b32 s64, s26, s28
	s_cselect_b32 s65, s27, s29
	s_cselect_b32 s14, 0, 0x1000
	s_lshl_b32 s17, s10, 12
	s_lshl_b32 s18, s15, 8
	s_add_u32 s17, s17, s18
	s_sub_u32 s17, s17, s14
	s_add_u32 s64, s64, s17
	s_addc_u32 s65, s65, 0
	s_mov_b32 s69, 1
.Lpw_pdone_a:
	v_mad_u32_u24 v46, v40, s62, v43
	global_load_dwordx4 v[0:3], v46, s[60:61]
	v_add_u32_e32 v46, s63, v46
	global_load_dwordx4 v[4:7], v46, s[60:61]
	v_add_u32_e32 v46, s63, v46
	global_load_dwordx4 v[8:11], v46, s[60:61]
	v_add_u32_e32 v46, s63, v46
	global_load_dwordx4 v[12:15], v46, s[60:61]
	v_add_u32_e32 v46, s63, v46
	global_load_dwordx4 v[16:19], v46, s[60:61]
	v_add_u32_e32 v46, s63, v46
	global_load_dwordx4 v[20:23], v46, s[60:61]
	v_add_u32_e32 v46, s63, v46
	global_load_dwordx4 v[24:27], v46, s[60:61]
	v_add_u32_e32 v46, s63, v46
	global_load_dwordx4 v[28:31], v46, s[60:61]
	s_cmp_eq_u32 s69, 0
	s_cbranch_scc1 .Lpw_nog_a
	global_load_dword v32, v44, s[64:65]
	global_load_dword v33, v44, s[64:65] offset:32
	global_load_dword v34, v44, s[64:65] offset:64
	global_load_dword v35, v44, s[64:65] offset:96
	global_load_dword v36, v44, s[64:65] offset:128
	global_load_dword v37, v44, s[64:65] offset:160
	global_load_dword v38, v44, s[64:65] offset:192
	global_load_dword v39, v44, s[64:65] offset:224
.Lpw_nog_a:
	s_mov_b64 s[52:53], s[66:67]
	s_mov_b32 s54, s68
	s_mov_b32 s55, s70
	s_mov_b32 s56, s69
	s_waitcnt vmcnt(0)
	s_branch .Lpw_body

.Lpw_body:
	s_cmp_eq_u32 s56, 0
	s_cbranch_scc1 .Lpw_nomul
	v_mul_f32_e32 v0, v32, v0
	v_mul_f32_e32 v1, v32, v1
	v_mul_f32_e32 v2, v32, v2
	v_mul_f32_e32 v3, v32, v3
	v_mul_f32_e32 v4, v33, v4
	v_mul_f32_e32 v5, v33, v5
	v_mul_f32_e32 v6, v33, v6
	v_mul_f32_e32 v7, v33, v7
	v_mul_f32_e32 v8, v34, v8
	v_mul_f32_e32 v9, v34, v9
	v_mul_f32_e32 v10, v34, v10
	v_mul_f32_e32 v11, v34, v11
	v_mul_f32_e32 v12, v35, v12
	v_mul_f32_e32 v13, v35, v13
	v_mul_f32_e32 v14, v35, v14
	v_mul_f32_e32 v15, v35, v15
	v_mul_f32_e32 v16, v36, v16
	v_mul_f32_e32 v17, v36, v17
	v_mul_f32_e32 v18, v36, v18
	v_mul_f32_e32 v19, v36, v19
	v_mul_f32_e32 v20, v37, v20
	v_mul_f32_e32 v21, v37, v21
	v_mul_f32_e32 v22, v37, v22
	v_mul_f32_e32 v23, v37, v23
	v_mul_f32_e32 v24, v38, v24
	v_mul_f32_e32 v25, v38, v25
	v_mul_f32_e32 v26, v38, v26
	v_mul_f32_e32 v27, v38, v27
	v_mul_f32_e32 v28, v39, v28
	v_mul_f32_e32 v29, v39, v29
	v_mul_f32_e32 v30, v39, v30
	v_mul_f32_e32 v31, v39, v31
.Lpw_nomul:
	ds_write_b32 v42, v0
	ds_write_b32 v42, v1 offset:4
	ds_write_b32 v42, v2 offset:8
	ds_write_b32 v42, v3 offset:12
	ds_write_b32 v42, v4 offset:1056
	ds_write_b32 v42, v5 offset:1060
	ds_write_b32 v42, v6 offset:1064
	ds_write_b32 v42, v7 offset:1068
	ds_write_b32 v42, v8 offset:2112
	ds_write_b32 v42, v9 offset:2116
	ds_write_b32 v42, v10 offset:2120
	ds_write_b32 v42, v11 offset:2124
	ds_write_b32 v42, v12 offset:3168
	ds_write_b32 v42, v13 offset:3172
	ds_write_b32 v42, v14 offset:3176
	ds_write_b32 v42, v15 offset:3180
	ds_write_b32 v42, v16 offset:4224
	ds_write_b32 v42, v17 offset:4228
	ds_write_b32 v42, v18 offset:4232
	ds_write_b32 v42, v19 offset:4236
	ds_write_b32 v42, v20 offset:5280
	ds_write_b32 v42, v21 offset:5284
	ds_write_b32 v42, v22 offset:5288
	ds_write_b32 v42, v23 offset:5292
	ds_write_b32 v42, v24 offset:6336
	ds_write_b32 v42, v25 offset:6340
	ds_write_b32 v42, v26 offset:6344
	ds_write_b32 v42, v27 offset:6348
	ds_write_b32 v42, v28 offset:7392
	ds_write_b32 v42, v29 offset:7396
	ds_write_b32 v42, v30 offset:7400
	ds_write_b32 v42, v31 offset:7404
	s_add_u32 s51, s51, s30
	s_cmp_lt_u32 s51, 0x13000
	s_cbranch_scc0 .Lpw_last

	s_cmp_ge_u32 s51, 0x9800
	s_cselect_b32 s10, 1, 0
	s_mul_i32 s11, s10, 0x9800
	s_sub_u32 s11, s51, s11
	s_mul_i32 s12, s10, 0xa000000
	s_add_u32 s66, s3, s12
	s_addc_u32 s67, s8, 0
	s_mov_b32 s69, 0
	s_cmp_lt_u32 s11, 0x5800
	s_cbranch_scc0 .Lpw_notgu_b
	s_cmp_ge_u32 s11, 0x2c00
	s_cselect_b32 s13, 1, 0
	s_cselect_b32 s60, s20, s44
	s_cselect_b32 s61, s21, s45
	s_mul_i32 s14, s13, 0x2c00
	s_sub_u32 s11, s11, s14
	s_mul_hi_u32 s15, s11, 0xba2e8c
	s_mul_i32 s14, s15, 0x160
	s_sub_u32 s16, s11, s14
	s_lshl_b32 s16, s16, 5
	s_mul_i32 s14, s10, 0x5800000
	s_add_u32 s60, s60, s14
	s_addc_u32 s61, s61, 0
	s_mul_i32 s14, s15, 0x2c0000
	s_add_u32 s60, s60, s14
	s_addc_u32 s61, s61, 0
	s_lshl_b32 s14, s16, 2
	s_add_u32 s60, s60, s14
	s_addc_u32 s61, s61, 0
	s_mov_b32 s62, 0xb000
	s_mov_b32 s63, 0x58000
	s_cmp_ge_u32 s16, 0x1600
	s_cselect_b32 s17, 1, 0
	s_mul_i32 s18, s17, 0x1600
	s_sub_u32 s18, s16, s18
	s_lshr_b32 s19, s18, 7
	s_lshl_b32 s19, s19, 8
	s_lshl_b32 s14, s17, 7
	s_add_u32 s19, s19, s14
	s_and_b32 s14, s18, 0x7f
	s_add_u32 s19, s19, s14
	s_mul_i32 s14, s13, 0x2c00000
	s_add_u32 s66, s66, s14
	s_addc_u32 s67, s67, 0
	s_lshl_b32 s14, s19, 12
	s_add_u32 s66, s66, s14
	s_addc_u32 s67, s67, 0
	s_lshl_b32 s14, s15, 7
	s_add_u32 s66, s66, s14
	s_addc_u32 s67, s67, 0
	s_movk_i32 s68, 0x1000
	s_mov_b32 s70, 0x8000
	s_branch .Lpw_pdone_b

.Lpw_pdone_b:
	s_waitcnt lgkmcnt(0)
	v_mad_u32_u24 v46, v40, s62, v43
	global_load_dwordx4 v[0:3], v46, s[60:61]
	v_add_u32_e32 v46, s63, v46
	global_load_dwordx4 v[4:7], v46, s[60:61]
	v_add_u32_e32 v46, s63, v46
	global_load_dwordx4 v[8:11], v46, s[60:61]
	v_add_u32_e32 v46, s63, v46
	global_load_dwordx4 v[12:15], v46, s[60:61]
	v_add_u32_e32 v46, s63, v46
	global_load_dwordx4 v[16:19], v46, s[60:61]
	v_add_u32_e32 v46, s63, v46
	global_load_dwordx4 v[20:23], v46, s[60:61]
	v_add_u32_e32 v46, s63, v46
	global_load_dwordx4 v[24:27], v46, s[60:61]
	v_add_u32_e32 v46, s63, v46
	global_load_dwordx4 v[28:31], v46, s[60:61]
	s_cmp_eq_u32 s69, 0
	s_cbranch_scc1 .Lpw_nog_b
	global_load_dword v32, v44, s[64:65]
	global_load_dword v33, v44, s[64:65] offset:32
	global_load_dword v34, v44, s[64:65] offset:64
	global_load_dword v35, v44, s[64:65] offset:96
	global_load_dword v36, v44, s[64:65] offset:128
	global_load_dword v37, v44, s[64:65] offset:160
	global_load_dword v38, v44, s[64:65] offset:192
	global_load_dword v39, v44, s[64:65] offset:224
.Lpw_nog_b:
	ds_read2_b32 v[64:65], v45 offset0:0 offset1:33
	ds_read2_b32 v[66:67], v45 offset0:66 offset1:99
	ds_read2_b32 v[68:69], v45 offset0:132 offset1:165
	ds_read2_b32 v[70:71], v45 offset0:198 offset1:231
	ds_read2_b32 v[72:73], v45 offset0:8 offset1:41
	ds_read2_b32 v[74:75], v45 offset0:74 offset1:107
	ds_read2_b32 v[76:77], v45 offset0:140 offset1:173
	ds_read2_b32 v[78:79], v45 offset0:206 offset1:239
	ds_read2_b32 v[80:81], v45 offset0:16 offset1:49
	ds_read2_b32 v[82:83], v45 offset0:82 offset1:115
	ds_read2_b32 v[84:85], v45 offset0:148 offset1:181
	ds_read2_b32 v[86:87], v45 offset0:214 offset1:247
	ds_read2_b32 v[88:89], v45 offset0:24 offset1:57
	ds_read2_b32 v[90:91], v45 offset0:90 offset1:123
	ds_read2_b32 v[92:93], v45 offset0:156 offset1:189
	ds_read2_b32 v[94:95], v45 offset0:222 offset1:255
	v_mad_u32_u24 v47, v40, s54, v43
	s_waitcnt lgkmcnt(0)
	v_cvt_pk_bf16_f32 v64, v64, v65
	v_cvt_pk_bf16_f32 v65, v66, v67
	v_cvt_pk_bf16_f32 v66, v68, v69
	v_cvt_pk_bf16_f32 v67, v70, v71
	v_cvt_pk_bf16_f32 v72, v72, v73
	v_cvt_pk_bf16_f32 v73, v74, v75
	v_cvt_pk_bf16_f32 v74, v76, v77
	v_cvt_pk_bf16_f32 v75, v78, v79
	v_cvt_pk_bf16_f32 v80, v80, v81
	v_cvt_pk_bf16_f32 v81, v82, v83
	v_cvt_pk_bf16_f32 v82, v84, v85
	v_cvt_pk_bf16_f32 v83, v86, v87
	v_cvt_pk_bf16_f32 v88, v88, v89
	v_cvt_pk_bf16_f32 v89, v90, v91
	v_cvt_pk_bf16_f32 v90, v92, v93
	v_cvt_pk_bf16_f32 v91, v94, v95
	global_store_dwordx4 v47, v[64:67], s[52:53]
	v_add_u32_e32 v47, s55, v47
	global_store_dwordx4 v47, v[72:75], s[52:53]
	v_add_u32_e32 v47, s55, v47
	global_store_dwordx4 v47, v[80:83], s[52:53]
	v_add_u32_e32 v47, s55, v47
	global_store_dwordx4 v47, v[88:91], s[52:53]
	s_mov_b64 s[52:53], s[66:67]
	s_mov_b32 s54, s68
	s_mov_b32 s55, s70
	s_mov_b32 s56, s69
	s_branch .Lpw_loop
.Lpw_last:
	s_waitcnt lgkmcnt(0)
	ds_read2_b32 v[64:65], v45 offset0:0 offset1:33
	ds_read2_b32 v[66:67], v45 offset0:66 offset1:99
	ds_read2_b32 v[68:69], v45 offset0:132 offset1:165
	ds_read2_b32 v[70:71], v45 offset0:198 offset1:231
	ds_read2_b32 v[72:73], v45 offset0:8 offset1:41
	ds_read2_b32 v[74:75], v45 offset0:74 offset1:107
	ds_read2_b32 v[76:77], v45 offset0:140 offset1:173
	ds_read2_b32 v[78:79], v45 offset0:206 offset1:239
	ds_read2_b32 v[80:81], v45 offset0:16 offset1:49
	ds_read2_b32 v[82:83], v45 offset0:82 offset1:115
	ds_read2_b32 v[84:85], v45 offset0:148 offset1:181
	ds_read2_b32 v[86:87], v45 offset0:214 offset1:247
	ds_read2_b32 v[88:89], v45 offset0:24 offset1:57
	ds_read2_b32 v[90:91], v45 offset0:90 offset1:123
	ds_read2_b32 v[92:93], v45 offset0:156 offset1:189
	ds_read2_b32 v[94:95], v45 offset0:222 offset1:255
	v_mad_u32_u24 v47, v40, s54, v43
	s_waitcnt lgkmcnt(0)
	v_cvt_pk_bf16_f32 v64, v64, v65
	v_cvt_pk_bf16_f32 v65, v66, v67
	v_cvt_pk_bf16_f32 v66, v68, v69
	v_cvt_pk_bf16_f32 v67, v70, v71
	v_cvt_pk_bf16_f32 v72, v72, v73
	v_cvt_pk_bf16_f32 v73, v74, v75
	v_cvt_pk_bf16_f32 v74, v76, v77
	v_cvt_pk_bf16_f32 v75, v78, v79
	v_cvt_pk_bf16_f32 v80, v80, v81
	v_cvt_pk_bf16_f32 v81, v82, v83
	v_cvt_pk_bf16_f32 v82, v84, v85
	v_cvt_pk_bf16_f32 v83, v86, v87
	v_cvt_pk_bf16_f32 v88, v88, v89
	v_cvt_pk_bf16_f32 v89, v90, v91
	v_cvt_pk_bf16_f32 v90, v92, v93
	v_cvt_pk_bf16_f32 v91, v94, v95
	global_store_dwordx4 v47, v[64:67], s[52:53]
	v_add_u32_e32 v47, s55, v47
	global_store_dwordx4 v47, v[72:75], s[52:53]
	v_add_u32_e32 v47, s55, v47
	global_store_dwordx4 v47, v[80:83], s[52:53]
	v_add_u32_e32 v47, s55, v47
	global_store_dwordx4 v47, v[88:91], s[52:53]
	v_readlane_b32 s0, v255, 22
	v_readlane_b32 s1, v255, 23
